# P8 epilogue + P9: gelu argument K(x + c x^3) in 3 VALU ops (x*x, fmaak with c*K in v254, x*t) instead of 4
# speedup vs baseline: 1.0010x; 1.0010x over previous
; __device__ __forceinline__ u32x4 pack8(const f32x4 a, const f32x4 b) { u32x4 w; w.x = cvt_pk_bf16(a[0], a[1]); w.y = cvt_pk_bf16(a[2], a[3]); w.z = cvt_pk_bf16(b[0], b[1]); w.w = cvt_pk_bf16(b[2], b[3]); return w; }
;     __device__ __forceinline__ void operator()(const f32x4 (&acc)[2][2][4][2], const Unit& u, int wr, int wc, int fr, int fq) const {
;     ...
;         const int f0 = u.pn * 128 + wc * 32 + 8 * fq;
;         f32x4 w0[2], w1[2], w2[2], bb[2];
; #pragma unroll
;         for (int n = 0; n < 2; ++n) { w0[n] = *(const f32x4*)(cw + f0 + 4 * n); w1[n] = *(const f32x4*)(cw + DFF + f0 + 4 * n); w2[n] = *(const f32x4*)(cw + 2 * DFF + f0 + 4 * n); bb[n] = *(const f32x4*)(cb + f0 + 4 * n); }
;         const int src1 = (lane & 48) | ((fr - 1) & 15), src2 = (lane & 48) | ((fr - 2) & 15);
; #pragma unroll
;         for (int ai = 0; ai < 2; ++ai) {
;             const int jb = u.pm * 4 + ai * 2 + wr;
;             f32x4 p1[2], p2[2];
; #pragma unroll
;             for (int n = 0; n < 2; ++n) { p1[n] = (f32x4){0.f, 0.f, 0.f, 0.f}; p2[n] = p1[n]; }
; #pragma unroll
;             for (int m = 0; m < 4; ++m) {
;                 f32x4 o[2];
; #pragma unroll
;                 for (int n = 0; n < 2; ++n) { f32x4 r1, r2;
; #pragma unroll
;                     for (int e = 0; e < 4; ++e) { const float a0 = acc[ai][0][m][n][e]; r1[e] = __shfl(a0, src1); r2[e] = __shfl(a0, src2); }
;                     f32x4 a1, a2;
; #pragma unroll
;                     for (int e = 0; e < 4; ++e) { a1[e] = fr >= 1 ? r1[e] : p1[n][e]; a2[e] = fr >= 2 ? r2[e] : p2[n][e]; }
;                     p1[n] = r1; p2[n] = r2;
;                     const f32x4 c = bb[n] + w0[n] * a2 + w1[n] * a1 + w2[n] * acc[ai][0][m][n];
; #pragma unroll
;                     for (int e = 0; e < 4; ++e) { const float x = c[e]; const float uu = 0.7978845608028654f * (x + 0.044715f * x * x * x);
;                         const float gl = x * __builtin_amdgcn_rcpf(1.f + __builtin_amdgcn_exp2f(-2.885390081777927f * uu)); o[n][e] = gl * acc[ai][1][m][n][e]; } }
;                 const int row = u.pm * BM + ai * HALF + wr * 64 + m * 16 + fr;
;                 if (!(m == 0 && fr < 2)) *(u32x4*)(G + (size_t)row * DFF + f0) = pack8(o[0], o[1]);
.LBB0_911:
	v_mov_b32_e32 v254, 0xbdd2d3e7
	v_lshl_or_b32 v186, s67, 7, v175
	v_ashrrev_i32_e32 v187, 31, v186
	v_lshlrev_b64 v[188:189], 2, v[186:187]
	v_lshl_add_u64 v[86:87], s[24:25], 0, v[188:189]
	v_lshl_add_u64 v[90:91], s[40:41], 0, v[188:189]
	v_lshl_add_u64 v[94:95], s[44:45], 0, v[188:189]
	v_lshl_add_u64 v[110:111], s[26:27], 0, v[188:189]
	global_load_dwordx4 v[82:85], v[86:87], off offset:16
	global_load_dwordx4 v[98:101], v[86:87], off
	s_nop 0
	global_load_dwordx4 v[86:89], v[90:91], off offset:16
	global_load_dwordx4 v[102:105], v[90:91], off
	s_nop 0
	global_load_dwordx4 v[90:93], v[94:95], off offset:16
	global_load_dwordx4 v[106:109], v[94:95], off
	s_nop 0
	global_load_dwordx4 v[94:97], v[110:111], off offset:16
	s_nop 0
	global_load_dwordx4 v[110:113], v[110:111], off
	ds_bpermute_b32 v200, v212, v158
	ds_bpermute_b32 v198, v213, v158
	ds_bpermute_b32 v201, v212, v159
	ds_bpermute_b32 v199, v213, v159
	ds_bpermute_b32 v196, v212, v160
	ds_bpermute_b32 v194, v213, v160
	ds_bpermute_b32 v197, v212, v161
	ds_bpermute_b32 v195, v213, v161
	ds_bpermute_b32 v192, v212, v154
	ds_bpermute_b32 v190, v213, v154
	ds_bpermute_b32 v193, v212, v155
	ds_bpermute_b32 v191, v213, v155
	ds_bpermute_b32 v204, v212, v156
	ds_bpermute_b32 v202, v213, v156
	ds_bpermute_b32 v205, v212, v157
	ds_bpermute_b32 v203, v213, v157
	v_lshl_add_u32 v215, s66, 8, v165
	s_and_saveexec_b64 s[68:69], s[8:9]
	s_xor_b64 s[68:69], exec, s[68:69]
	s_cbranch_execz .LBB0_913
	s_waitcnt vmcnt(0) lgkmcnt(0)
	v_pk_fma_f32 v[216:217], v[84:85], v[202:203], v[96:97]
	s_nop 0
	v_pk_fma_f32 v[216:217], v[88:89], v[204:205], v[216:217]
	s_nop 0
	v_pk_fma_f32 v[216:217], v[156:157], v[92:93], v[216:217]
	s_nop 0
	v_mul_f32_e32 v218, v217, v217
	v_fmaak_f32 v218, v254, v218, 0xc0135761
	v_mul_f32_e32 v219, v216, v216
	v_mul_f32_e32 v218, v217, v218
	v_fmaak_f32 v219, v254, v219, 0xc0135761
	v_mul_f32_e32 v219, v216, v219
	v_exp_f32_e32 v218, v218
	v_exp_f32_e32 v220, v219
	v_add_f32_e32 v218, 1.0, v218
	v_rcp_f32_e32 v219, v218
	v_add_f32_e32 v218, 1.0, v220
	v_rcp_f32_e32 v218, v218
	s_nop 0
	v_pk_mul_f32 v[216:217], v[216:217], v[218:219]
	v_pk_fma_f32 v[218:219], v[98:99], v[198:199], v[110:111]
	s_nop 0
	v_pk_fma_f32 v[218:219], v[102:103], v[200:201], v[218:219]
	s_nop 0
	v_pk_fma_f32 v[218:219], v[158:159], v[106:107], v[218:219]
	s_nop 0
	v_mul_f32_e32 v220, v218, v218
	v_fmaak_f32 v220, v254, v220, 0xc0135761
	v_mul_f32_e32 v220, v218, v220
	v_exp_f32_e32 v222, v220
	v_mul_f32_e32 v220, v219, v219
	v_fmaak_f32 v220, v254, v220, 0xc0135761
	v_mul_f32_e32 v220, v219, v220
	v_exp_f32_e32 v223, v220
	v_pk_mul_f32 v[220:221], v[148:149], v[216:217]
	v_add_f32_e32 v216, 1.0, v222
	v_rcp_f32_e32 v216, v216
	v_add_f32_e32 v217, 1.0, v223
	v_pk_fma_f32 v[222:223], v[100:101], v[194:195], v[112:113]
	v_rcp_f32_e32 v217, v217
	v_pk_fma_f32 v[222:223], v[104:105], v[196:197], v[222:223]
	v_pk_mul_f32 v[216:217], v[218:219], v[216:217]
	v_pk_fma_f32 v[222:223], v[160:161], v[108:109], v[222:223]
	v_pk_mul_f32 v[216:217], v[150:151], v[216:217]
	v_mul_f32_e32 v224, v222, v222
	v_mul_f32_e32 v225, v223, v223
	v_fmaak_f32 v224, v254, v224, 0xc0135761
	v_fmaak_f32 v225, v254, v225, 0xc0135761
	v_mul_f32_e32 v224, v222, v224
	v_mul_f32_e32 v225, v223, v225
	v_exp_f32_e32 v224, v224
	v_exp_f32_e32 v225, v225
	v_cvt_pk_bf16_f32 v216, v216, v217
	v_add_f32_e32 v218, 1.0, v224
	v_add_f32_e32 v219, 1.0, v225
	v_pk_fma_f32 v[224:225], v[82:83], v[190:191], v[94:95]
	v_rcp_f32_e32 v218, v218
	v_pk_fma_f32 v[224:225], v[86:87], v[192:193], v[224:225]
	v_rcp_f32_e32 v219, v219
	v_pk_fma_f32 v[224:225], v[154:155], v[90:91], v[224:225]
	v_pk_mul_f32 v[218:219], v[222:223], v[218:219]
	v_mul_f32_e32 v226, v225, v225
	v_fmaak_f32 v226, v254, v226, 0xc0135761
	v_mul_f32_e32 v227, v224, v224
	v_mul_f32_e32 v226, v225, v226
	v_fmaak_f32 v227, v254, v227, 0xc0135761
	v_mul_f32_e32 v227, v224, v227
	v_exp_f32_e32 v226, v226
	v_exp_f32_e32 v228, v227
	v_pk_mul_f32 v[218:219], v[152:153], v[218:219]
	v_add_f32_e32 v226, 1.0, v226
	v_rcp_f32_e32 v227, v226
	v_add_f32_e32 v226, 1.0, v228
	v_rcp_f32_e32 v226, v226
	v_cvt_pk_bf16_f32 v217, v218, v219
	v_cvt_pk_bf16_f32 v219, v220, v221
	v_mov_b64_e32 v[220:221], s[10:11]
	v_pk_mul_f32 v[222:223], v[224:225], v[226:227]
	v_mad_i64_i32 v[220:221], s[70:71], v215, s79, v[220:221]
	v_pk_mul_f32 v[222:223], v[146:147], v[222:223]
	v_lshl_add_u64 v[220:221], v[186:187], 1, v[220:221]
	v_cvt_pk_bf16_f32 v218, v222, v223
	global_store_dwordx4 v[220:221], v[216:219], off

; __device__ __forceinline__ u32x4 pack8(const f32x4 a, const f32x4 b) { u32x4 w; w.x = cvt_pk_bf16(a[0], a[1]); w.y = cvt_pk_bf16(a[2], a[3]); w.z = cvt_pk_bf16(b[0], b[1]); w.w = cvt_pk_bf16(b[2], b[3]); return w; }
;     __device__ __forceinline__ void operator()(const f32x4 (&acc)[2][2][4][2], const Unit& u, int wr, int wc, int fr, int fq) const {
;     ...
;             for (int m = 0; m < 4; ++m) {
;                 f32x4 o[2];
; #pragma unroll
;                 for (int n = 0; n < 2; ++n) { f32x4 r1, r2;
; #pragma unroll
;                     for (int e = 0; e < 4; ++e) { const float a0 = acc[ai][0][m][n][e]; r1[e] = __shfl(a0, src1); r2[e] = __shfl(a0, src2); }
;                     f32x4 a1, a2;
; #pragma unroll
;                     for (int e = 0; e < 4; ++e) { a1[e] = fr >= 1 ? r1[e] : p1[n][e]; a2[e] = fr >= 2 ? r2[e] : p2[n][e]; }
;                     p1[n] = r1; p2[n] = r2;
;                     const f32x4 c = bb[n] + w0[n] * a2 + w1[n] * a1 + w2[n] * acc[ai][0][m][n];
; #pragma unroll
;                     for (int e = 0; e < 4; ++e) { const float x = c[e]; const float uu = 0.7978845608028654f * (x + 0.044715f * x * x * x);
;                         const float gl = x * __builtin_amdgcn_rcpf(1.f + __builtin_amdgcn_exp2f(-2.885390081777927f * uu)); o[n][e] = gl * acc[ai][1][m][n][e]; } }
;                 const int row = u.pm * BM + ai * HALF + wr * 64 + m * 16 + fr;
;                 if (!(m == 0 && fr < 2)) *(u32x4*)(G + (size_t)row * DFF + f0) = pack8(o[0], o[1]);
.LBB0_915:
	s_or_b64 exec, exec, s[70:71]
	ds_bpermute_b32 v159, v213, v141
	ds_bpermute_b32 v160, v213, v140
	ds_bpermute_b32 v157, v212, v141
	ds_bpermute_b32 v158, v212, v140
	ds_bpermute_b32 v151, v213, v142
	s_waitcnt lgkmcnt(0)
	v_cndmask_b32_e64 v149, v203, v159, s[8:9]
	v_cndmask_b32_e64 v148, v202, v160, s[8:9]
	v_cndmask_b32_e64 v147, v157, v205, s[0:1]
	v_cndmask_b32_e64 v146, v158, v204, s[0:1]
	s_waitcnt vmcnt(0)
	v_pk_fma_f32 v[148:149], v[84:85], v[148:149], v[96:97]
	ds_bpermute_b32 v153, v213, v143
	v_pk_fma_f32 v[146:147], v[88:89], v[146:147], v[148:149]
	ds_bpermute_b32 v150, v212, v142
	v_pk_fma_f32 v[140:141], v[140:141], v[92:93], v[146:147]
	ds_bpermute_b32 v152, v212, v143
	v_mul_f32_e32 v146, v141, v141
	v_fmaak_f32 v146, v254, v146, 0xc0135761
	v_mul_f32_e32 v147, v140, v140
	v_mul_f32_e32 v146, v141, v146
	v_fmaak_f32 v147, v254, v147, 0xc0135761
	v_mul_f32_e32 v147, v140, v147
	v_exp_f32_e32 v146, v146
	v_exp_f32_e32 v148, v147
	s_waitcnt lgkmcnt(2)
	v_cndmask_b32_e64 v149, v199, v153, s[8:9]
	v_add_f32_e32 v146, 1.0, v146
	v_rcp_f32_e32 v147, v146
	v_add_f32_e32 v146, 1.0, v148
	v_rcp_f32_e32 v146, v146
	v_cndmask_b32_e64 v148, v198, v151, s[8:9]
	v_pk_fma_f32 v[148:149], v[98:99], v[148:149], v[110:111]
	ds_bpermute_b32 v155, v213, v144
	v_pk_mul_f32 v[140:141], v[140:141], v[146:147]
	s_waitcnt lgkmcnt(1)
	v_cndmask_b32_e64 v147, v152, v201, s[0:1]
	v_cndmask_b32_e64 v146, v150, v200, s[0:1]
	v_pk_fma_f32 v[146:147], v[102:103], v[146:147], v[148:149]
	ds_bpermute_b32 v161, v213, v145
	v_pk_fma_f32 v[142:143], v[142:143], v[106:107], v[146:147]
	ds_bpermute_b32 v154, v212, v144
	v_mul_f32_e32 v146, v142, v142
	v_mul_f32_e32 v147, v143, v143
	v_fmaak_f32 v146, v254, v146, 0xc0135761
	v_fmaak_f32 v147, v254, v147, 0xc0135761
	v_mul_f32_e32 v146, v142, v146
	v_mul_f32_e32 v147, v143, v147
	ds_bpermute_b32 v156, v212, v145
	v_exp_f32_e32 v146, v146
	v_exp_f32_e32 v147, v147
	s_waitcnt lgkmcnt(2)
	v_cndmask_b32_e64 v149, v195, v161, s[8:9]
	v_cndmask_b32_e64 v148, v194, v155, s[8:9]
	v_pk_mul_f32 v[132:133], v[132:133], v[140:141]
	v_add_f32_e32 v140, 1.0, v146
	v_add_f32_e32 v141, 1.0, v147
	s_waitcnt lgkmcnt(0)
	v_cndmask_b32_e64 v147, v156, v197, s[0:1]
	v_cndmask_b32_e64 v146, v154, v196, s[0:1]
	v_pk_fma_f32 v[148:149], v[100:101], v[148:149], v[112:113]
	ds_bpermute_b32 v203, v213, v138
	v_pk_fma_f32 v[146:147], v[104:105], v[146:147], v[148:149]
	ds_bpermute_b32 v205, v213, v139
	v_pk_fma_f32 v[144:145], v[144:145], v[108:109], v[146:147]
	ds_bpermute_b32 v202, v212, v138
	v_mul_f32_e32 v146, v144, v144
	v_mul_f32_e32 v147, v145, v145
	v_fmaak_f32 v146, v254, v146, 0xc0135761
	v_fmaak_f32 v147, v254, v147, 0xc0135761
	v_mul_f32_e32 v146, v144, v146
	v_mul_f32_e32 v147, v145, v147
	ds_bpermute_b32 v204, v212, v139
	v_rcp_f32_e32 v140, v140
	v_rcp_f32_e32 v141, v141
	v_exp_f32_e32 v146, v146
	v_exp_f32_e32 v147, v147
	s_waitcnt lgkmcnt(2)
	v_cndmask_b32_e64 v149, v191, v205, s[8:9]
	v_cndmask_b32_e64 v148, v190, v203, s[8:9]
	v_pk_mul_f32 v[140:141], v[142:143], v[140:141]
	v_add_f32_e32 v142, 1.0, v146
	v_add_f32_e32 v143, 1.0, v147
	s_waitcnt lgkmcnt(0)
	v_cndmask_b32_e64 v147, v204, v193, s[0:1]
	v_cndmask_b32_e64 v146, v202, v192, s[0:1]
	v_pk_fma_f32 v[148:149], v[82:83], v[148:149], v[94:95]
	v_rcp_f32_e32 v142, v142
	v_pk_fma_f32 v[146:147], v[86:87], v[146:147], v[148:149]
	v_rcp_f32_e32 v143, v143
	v_pk_fma_f32 v[138:139], v[138:139], v[90:91], v[146:147]
	v_pk_mul_f32 v[134:135], v[134:135], v[140:141]
	v_mul_f32_e32 v146, v139, v139
	v_fmaak_f32 v146, v254, v146, 0xc0135761
	v_mul_f32_e32 v147, v138, v138
	v_mul_f32_e32 v146, v139, v146
	v_fmaak_f32 v147, v254, v147, 0xc0135761
	v_mul_f32_e32 v147, v138, v147
	v_exp_f32_e32 v146, v146
	v_exp_f32_e32 v148, v147
	v_pk_mul_f32 v[140:141], v[144:145], v[142:143]
	v_add_f32_e32 v146, 1.0, v146
	v_rcp_f32_e32 v147, v146
	v_add_f32_e32 v146, 1.0, v148
	v_rcp_f32_e32 v146, v146
	ds_bpermute_b32 v148, v213, v124
	v_pk_mul_f32 v[136:137], v[136:137], v[140:141]
	ds_bpermute_b32 v145, v212, v125
	v_pk_mul_f32 v[138:139], v[138:139], v[146:147]
	ds_bpermute_b32 v147, v213, v125
	ds_bpermute_b32 v146, v212, v124
	v_pk_mul_f32 v[130:131], v[130:131], v[138:139]
	v_or_b32_e32 v138, 16, v215
	v_cvt_pk_bf16_f32 v134, v134, v135
	v_cvt_pk_bf16_f32 v135, v136, v137
	v_cvt_pk_bf16_f32 v137, v132, v133
	v_mov_b64_e32 v[132:133], s[10:11]
	v_cvt_pk_bf16_f32 v136, v130, v131
	v_mad_i64_i32 v[138:139], s[70:71], v138, s79, v[132:133]
	v_lshlrev_b64 v[130:131], 1, v[186:187]
	v_lshl_add_u64 v[138:139], v[138:139], 0, v[130:131]
	global_store_dwordx4 v[138:139], v[134:137], off
	ds_bpermute_b32 v139, v213, v126
	ds_bpermute_b32 v141, v213, v127
	s_waitcnt lgkmcnt(3)
	v_cndmask_b32_e64 v137, v159, v147, s[8:9]
	v_cndmask_b32_e64 v136, v160, v148, s[8:9]
	v_cndmask_b32_e64 v135, v145, v157, s[0:1]
	s_waitcnt lgkmcnt(2)
	v_cndmask_b32_e64 v134, v146, v158, s[0:1]
	v_pk_fma_f32 v[136:137], v[84:85], v[136:137], v[96:97]
	ds_bpermute_b32 v138, v212, v126
	v_pk_fma_f32 v[134:135], v[88:89], v[134:135], v[136:137]
	ds_bpermute_b32 v140, v212, v127
	v_pk_fma_f32 v[124:125], v[124:125], v[92:93], v[134:135]
	s_waitcnt lgkmcnt(2)
	v_cndmask_b32_e64 v137, v153, v141, s[8:9]
	v_mul_f32_e32 v134, v125, v125
	v_fmaak_f32 v134, v254, v134, 0xc0135761
	v_mul_f32_e32 v135, v124, v124
	v_mul_f32_e32 v134, v125, v134
	v_fmaak_f32 v135, v254, v135, 0xc0135761
	v_mul_f32_e32 v135, v124, v135
	v_exp_f32_e32 v134, v134
	v_exp_f32_e32 v136, v135
	ds_bpermute_b32 v143, v213, v128
	v_add_f32_e32 v134, 1.0, v134
	v_rcp_f32_e32 v135, v134
	v_add_f32_e32 v134, 1.0, v136
	v_rcp_f32_e32 v134, v134
	v_cndmask_b32_e64 v136, v151, v139, s[8:9]
	v_pk_fma_f32 v[136:137], v[98:99], v[136:137], v[110:111]
	ds_bpermute_b32 v149, v213, v129
	v_pk_mul_f32 v[124:125], v[124:125], v[134:135]
	s_waitcnt lgkmcnt(2)
; __device__ __forceinline__ u32x4 pack8(const f32x4 a, const f32x4 b) { u32x4 w; w.x = cvt_pk_bf16(a[0], a[1]); w.y = cvt_pk_bf16(a[2], a[3]); w.z = cvt_pk_bf16(b[0], b[1]); w.w = cvt_pk_bf16(b[2], b[3]); return w; }
;     __device__ __forceinline__ void operator()(const f32x4 (&acc)[2][2][4][2], const Unit& u, int wr, int wc, int fr, int fq) const {
;     ...
;             for (int m = 0; m < 4; ++m) {
;                 f32x4 o[2];
; #pragma unroll
;                 for (int n = 0; n < 2; ++n) { f32x4 r1, r2;
; #pragma unroll
;                     for (int e = 0; e < 4; ++e) { const float a0 = acc[ai][0][m][n][e]; r1[e] = __shfl(a0, src1); r2[e] = __shfl(a0, src2); }
;                     f32x4 a1, a2;
; #pragma unroll
;                     for (int e = 0; e < 4; ++e) { a1[e] = fr >= 1 ? r1[e] : p1[n][e]; a2[e] = fr >= 2 ? r2[e] : p2[n][e]; }
;                     p1[n] = r1; p2[n] = r2;
;                     const f32x4 c = bb[n] + w0[n] * a2 + w1[n] * a1 + w2[n] * acc[ai][0][m][n];
; #pragma unroll
;                     for (int e = 0; e < 4; ++e) { const float x = c[e]; const float uu = 0.7978845608028654f * (x + 0.044715f * x * x * x);
;                         const float gl = x * __builtin_amdgcn_rcpf(1.f + __builtin_amdgcn_exp2f(-2.885390081777927f * uu)); o[n][e] = gl * acc[ai][1][m][n][e]; } }
;                 const int row = u.pm * BM + ai * HALF + wr * 64 + m * 16 + fr;
;                 if (!(m == 0 && fr < 2)) *(u32x4*)(G + (size_t)row * DFF + f0) = pack8(o[0], o[1]);
	v_cndmask_b32_e64 v135, v140, v152, s[0:1]
	v_cndmask_b32_e64 v134, v138, v150, s[0:1]
	v_pk_fma_f32 v[134:135], v[102:103], v[134:135], v[136:137]
	ds_bpermute_b32 v142, v212, v128
	v_pk_fma_f32 v[126:127], v[126:127], v[106:107], v[134:135]
	ds_bpermute_b32 v144, v212, v129
	v_mul_f32_e32 v134, v126, v126
	v_mul_f32_e32 v135, v127, v127
	v_fmaak_f32 v134, v254, v134, 0xc0135761
	v_fmaak_f32 v135, v254, v135, 0xc0135761
	v_mul_f32_e32 v134, v126, v134
	v_mul_f32_e32 v135, v127, v135
	v_exp_f32_e32 v134, v134
	v_exp_f32_e32 v135, v135
	s_waitcnt lgkmcnt(2)
	v_cndmask_b32_e64 v137, v161, v149, s[8:9]
	v_cndmask_b32_e64 v136, v155, v143, s[8:9]
	v_pk_mul_f32 v[124:125], v[116:117], v[124:125]
	v_add_f32_e32 v116, 1.0, v134
	v_add_f32_e32 v117, 1.0, v135
	s_waitcnt lgkmcnt(0)
	v_cndmask_b32_e64 v135, v144, v156, s[0:1]
	v_cndmask_b32_e64 v134, v142, v154, s[0:1]
	v_pk_fma_f32 v[136:137], v[100:101], v[136:137], v[112:113]
	ds_bpermute_b32 v158, v213, v122
	v_pk_fma_f32 v[134:135], v[104:105], v[134:135], v[136:137]
	ds_bpermute_b32 v160, v213, v123
	v_pk_fma_f32 v[128:129], v[128:129], v[108:109], v[134:135]
	ds_bpermute_b32 v157, v212, v122
	v_mul_f32_e32 v134, v128, v128
	v_mul_f32_e32 v135, v129, v129
	v_fmaak_f32 v134, v254, v134, 0xc0135761
	v_fmaak_f32 v135, v254, v135, 0xc0135761
	v_mul_f32_e32 v134, v128, v134
	v_mul_f32_e32 v135, v129, v135
	ds_bpermute_b32 v159, v212, v123
	v_rcp_f32_e32 v116, v116
	v_rcp_f32_e32 v117, v117
	v_exp_f32_e32 v134, v134
	v_exp_f32_e32 v135, v135
	s_waitcnt lgkmcnt(2)
	v_cndmask_b32_e64 v137, v205, v160, s[8:9]
	v_cndmask_b32_e64 v136, v203, v158, s[8:9]
	v_pk_mul_f32 v[116:117], v[126:127], v[116:117]
	v_add_f32_e32 v126, 1.0, v134
	v_add_f32_e32 v127, 1.0, v135
	s_waitcnt lgkmcnt(0)
	v_cndmask_b32_e64 v135, v159, v204, s[0:1]
	v_cndmask_b32_e64 v134, v157, v202, s[0:1]
	v_pk_fma_f32 v[136:137], v[82:83], v[136:137], v[94:95]
	v_rcp_f32_e32 v126, v126
	v_pk_fma_f32 v[134:135], v[86:87], v[134:135], v[136:137]
	v_rcp_f32_e32 v127, v127
	v_pk_fma_f32 v[122:123], v[122:123], v[90:91], v[134:135]
	v_pk_mul_f32 v[116:117], v[118:119], v[116:117]
	v_mul_f32_e32 v134, v123, v123
	v_fmaak_f32 v134, v254, v134, 0xc0135761
	v_mul_f32_e32 v135, v122, v122
	v_mul_f32_e32 v134, v123, v134
	v_fmaak_f32 v135, v254, v135, 0xc0135761
	v_mul_f32_e32 v135, v122, v135
	v_exp_f32_e32 v134, v134
	v_exp_f32_e32 v136, v135
	v_pk_mul_f32 v[118:119], v[128:129], v[126:127]
	v_add_f32_e32 v134, 1.0, v134
	v_rcp_f32_e32 v135, v134
	v_add_f32_e32 v134, 1.0, v136
	v_rcp_f32_e32 v134, v134
	v_pk_mul_f32 v[118:119], v[120:121], v[118:119]
	ds_bpermute_b32 v126, v213, v81
	ds_bpermute_b32 v129, v213, v71
	v_pk_mul_f32 v[120:121], v[122:123], v[134:135]
	v_or_b32_e32 v122, 32, v215
	v_pk_mul_f32 v[120:121], v[114:115], v[120:121]
	v_cvt_pk_bf16_f32 v115, v118, v119
	v_mad_i64_i32 v[118:119], s[70:71], v122, s79, v[132:133]
	v_cvt_pk_bf16_f32 v114, v116, v117
	v_cvt_pk_bf16_f32 v116, v120, v121
	v_cvt_pk_bf16_f32 v117, v124, v125
	v_lshl_add_u64 v[118:119], v[118:119], 0, v[130:131]
	global_store_dwordx4 v[118:119], v[114:117], off
	ds_bpermute_b32 v114, v212, v73
	ds_bpermute_b32 v116, v212, v72
	ds_bpermute_b32 v117, v213, v73
	ds_bpermute_b32 v125, v213, v72
	ds_bpermute_b32 v118, v212, v78
	s_waitcnt lgkmcnt(4)
	v_cndmask_b32_e64 v115, v114, v145, s[0:1]
	s_waitcnt lgkmcnt(3)
	v_cndmask_b32_e64 v114, v116, v146, s[0:1]
	s_waitcnt lgkmcnt(2)
	v_cndmask_b32_e64 v117, v147, v117, s[8:9]
	s_waitcnt lgkmcnt(1)
	v_cndmask_b32_e64 v116, v148, v125, s[8:9]
	v_pk_fma_f32 v[116:117], v[84:85], v[116:117], v[96:97]
	ds_bpermute_b32 v120, v213, v78
	v_pk_fma_f32 v[114:115], v[88:89], v[114:115], v[116:117]
	ds_bpermute_b32 v119, v212, v79
	v_pk_fma_f32 v[114:115], v[72:73], v[92:93], v[114:115]
	ds_bpermute_b32 v121, v213, v79
	v_mul_f32_e32 v116, v115, v115
	v_fmaak_f32 v116, v254, v116, 0xc0135761
	v_mul_f32_e32 v117, v114, v114
	v_mul_f32_e32 v116, v115, v116
	v_fmaak_f32 v117, v254, v117, 0xc0135761
	v_mul_f32_e32 v117, v114, v117
	v_exp_f32_e32 v116, v116
	v_exp_f32_e32 v125, v117
	ds_bpermute_b32 v123, v213, v80
	v_add_f32_e32 v116, 1.0, v116
	v_rcp_f32_e32 v117, v116
	v_add_f32_e32 v116, 1.0, v125
	v_rcp_f32_e32 v116, v116
	ds_bpermute_b32 v122, v212, v80
	ds_bpermute_b32 v124, v212, v81
	ds_bpermute_b32 v125, v213, v70
	v_pk_mul_f32 v[114:115], v[114:115], v[116:117]
	s_waitcnt lgkmcnt(5)
	v_cndmask_b32_e64 v117, v119, v140, s[0:1]
	v_cndmask_b32_e64 v116, v118, v138, s[0:1]
	s_waitcnt lgkmcnt(4)
	v_cndmask_b32_e64 v119, v141, v121, s[8:9]
	v_cndmask_b32_e64 v118, v139, v120, s[8:9]
	v_pk_fma_f32 v[118:119], v[98:99], v[118:119], v[110:111]
	v_cndmask_b32_e64 v121, v149, v126, s[8:9]
	v_pk_fma_f32 v[116:117], v[102:103], v[116:117], v[118:119]
	s_waitcnt lgkmcnt(3)
	v_cndmask_b32_e64 v120, v143, v123, s[8:9]
	v_pk_fma_f32 v[116:117], v[78:79], v[106:107], v[116:117]
	v_pk_mul_f32 v[114:115], v[68:69], v[114:115]
	v_mul_f32_e32 v118, v116, v116
	v_mul_f32_e32 v119, v117, v117
	v_fmaak_f32 v118, v254, v118, 0xc0135761
	v_fmaak_f32 v119, v254, v119, 0xc0135761
	v_mul_f32_e32 v118, v116, v118
	v_mul_f32_e32 v119, v117, v119
	v_exp_f32_e32 v118, v118
	v_exp_f32_e32 v119, v119
	v_pk_fma_f32 v[120:121], v[100:101], v[120:121], v[112:113]
	ds_bpermute_b32 v127, v212, v70
	v_add_f32_e32 v68, 1.0, v118
	v_add_f32_e32 v69, 1.0, v119
	s_waitcnt lgkmcnt(2)
; __device__ __forceinline__ u32x4 pack8(const f32x4 a, const f32x4 b) { u32x4 w; w.x = cvt_pk_bf16(a[0], a[1]); w.y = cvt_pk_bf16(a[2], a[3]); w.z = cvt_pk_bf16(b[0], b[1]); w.w = cvt_pk_bf16(b[2], b[3]); return w; }
;     __device__ __forceinline__ void operator()(const f32x4 (&acc)[2][2][4][2], const Unit& u, int wr, int wc, int fr, int fq) const {
;     ...
;             for (int m = 0; m < 4; ++m) {
;                 f32x4 o[2];
; #pragma unroll
;                 for (int n = 0; n < 2; ++n) { f32x4 r1, r2;
; #pragma unroll
;                     for (int e = 0; e < 4; ++e) { const float a0 = acc[ai][0][m][n][e]; r1[e] = __shfl(a0, src1); r2[e] = __shfl(a0, src2); }
;                     f32x4 a1, a2;
; #pragma unroll
;                     for (int e = 0; e < 4; ++e) { a1[e] = fr >= 1 ? r1[e] : p1[n][e]; a2[e] = fr >= 2 ? r2[e] : p2[n][e]; }
;                     p1[n] = r1; p2[n] = r2;
;                     const f32x4 c = bb[n] + w0[n] * a2 + w1[n] * a1 + w2[n] * acc[ai][0][m][n];
; #pragma unroll
;                     for (int e = 0; e < 4; ++e) { const float x = c[e]; const float uu = 0.7978845608028654f * (x + 0.044715f * x * x * x);
;                         const float gl = x * __builtin_amdgcn_rcpf(1.f + __builtin_amdgcn_exp2f(-2.885390081777927f * uu)); o[n][e] = gl * acc[ai][1][m][n][e]; } }
;                 const int row = u.pm * BM + ai * HALF + wr * 64 + m * 16 + fr;
;                 if (!(m == 0 && fr < 2)) *(u32x4*)(G + (size_t)row * DFF + f0) = pack8(o[0], o[1]);
;                 if (m == 0 && fr < 2) { float* ah = AH + ((size_t)jb * 4 + 2 + fr) * DFF + f0; *(f32x4*)ah = acc[ai][0][0][0]; *(f32x4*)(ah + 4) = acc[ai][0][0][1];
;                     float* bh = BH + ((size_t)jb * 2 + fr) * DFF + f0; *(f32x4*)bh = acc[ai][1][0][0]; *(f32x4*)(bh + 4) = acc[ai][1][0][1]; }
;                 if (m == 3 && fr >= 14) { float* ah = AH + ((size_t)jb * 4 + (fr - 14)) * DFF + f0; *(f32x4*)ah = acc[ai][0][3][0]; *(f32x4*)(ah + 4) = acc[ai][0][3][1]; }
	v_cndmask_b32_e64 v119, v124, v144, s[0:1]
	v_cndmask_b32_e64 v118, v122, v142, s[0:1]
	v_pk_fma_f32 v[118:119], v[104:105], v[118:119], v[120:121]
	ds_bpermute_b32 v128, v212, v71
	v_pk_fma_f32 v[118:119], v[80:81], v[108:109], v[118:119]
	v_rcp_f32_e32 v68, v68
	v_mul_f32_e32 v120, v118, v118
	v_mul_f32_e32 v121, v119, v119
	v_fmaak_f32 v120, v254, v120, 0xc0135761
	v_fmaak_f32 v121, v254, v121, 0xc0135761
	v_mul_f32_e32 v120, v118, v120
	v_mul_f32_e32 v121, v119, v121
	v_rcp_f32_e32 v69, v69
	v_exp_f32_e32 v120, v120
	v_exp_f32_e32 v121, v121
	v_cndmask_b32_e64 v123, v160, v129, s[8:9]
	s_waitcnt lgkmcnt(2)
	v_cndmask_b32_e64 v122, v158, v125, s[8:9]
	v_pk_mul_f32 v[68:69], v[116:117], v[68:69]
	v_add_f32_e32 v116, 1.0, v120
	v_add_f32_e32 v117, 1.0, v121
	s_waitcnt lgkmcnt(0)
	v_cndmask_b32_e64 v121, v128, v159, s[0:1]
	v_cndmask_b32_e64 v120, v127, v157, s[0:1]
	v_pk_fma_f32 v[122:123], v[82:83], v[122:123], v[94:95]
	v_rcp_f32_e32 v116, v116
	v_pk_fma_f32 v[120:121], v[86:87], v[120:121], v[122:123]
	v_rcp_f32_e32 v117, v117
	v_pk_fma_f32 v[120:121], v[70:71], v[90:91], v[120:121]
	v_pk_mul_f32 v[68:69], v[74:75], v[68:69]
	v_mul_f32_e32 v122, v121, v121
	v_fmaak_f32 v122, v254, v122, 0xc0135761
	v_mul_f32_e32 v123, v120, v120
	v_mul_f32_e32 v122, v121, v122
	v_fmaak_f32 v123, v254, v123, 0xc0135761
	v_mul_f32_e32 v123, v120, v123
	v_exp_f32_e32 v122, v122
	v_exp_f32_e32 v124, v123
	v_pk_mul_f32 v[74:75], v[118:119], v[116:117]
	v_add_f32_e32 v122, 1.0, v122
	v_rcp_f32_e32 v123, v122
	v_add_f32_e32 v122, 1.0, v124
	v_rcp_f32_e32 v122, v122
	v_pk_mul_f32 v[74:75], v[76:77], v[74:75]
	v_or_b32_e32 v116, 48, v215
	v_pk_mul_f32 v[76:77], v[120:121], v[122:123]
	s_nop 0
	v_pk_mul_f32 v[76:77], v[66:67], v[76:77]
	v_cvt_pk_bf16_f32 v67, v74, v75
	v_mad_i64_i32 v[74:75], s[70:71], v116, s79, v[132:133]
	v_cvt_pk_bf16_f32 v66, v68, v69
	v_cvt_pk_bf16_f32 v68, v76, v77
	v_cvt_pk_bf16_f32 v69, v114, v115
	v_lshl_add_u64 v[74:75], v[74:75], 0, v[130:131]
	global_store_dwordx4 v[74:75], v[66:69], off
	s_and_saveexec_b64 s[70:71], s[4:5]
	s_cbranch_execz .LBB0_917
	v_lshl_add_u64 v[66:67], s[68:69], 0, v[176:177]
	v_mov_b64_e32 v[68:69], s[14:15]
	v_mad_u64_u32 v[68:69], s[68:69], v66, s80, v[68:69]
	v_mad_i32_i24 v69, v67, s80, v69
	v_lshl_add_u64 v[66:67], v[186:187], 2, v[68:69]
	global_store_dwordx4 v[66:67], v[78:81], off
	global_store_dwordx4 v[66:67], v[70:73], off offset:16
.LBB0_917:
	s_or_b64 exec, exec, s[70:71]
	ds_bpermute_b32 v76, v212, v62
	ds_bpermute_b32 v74, v213, v62
	ds_bpermute_b32 v77, v212, v63
	ds_bpermute_b32 v75, v213, v63
	ds_bpermute_b32 v72, v212, v64
	ds_bpermute_b32 v70, v213, v64
	ds_bpermute_b32 v73, v212, v65
	ds_bpermute_b32 v71, v213, v65
	ds_bpermute_b32 v68, v212, v58
	ds_bpermute_b32 v66, v213, v58
	ds_bpermute_b32 v69, v212, v59
	ds_bpermute_b32 v67, v213, v59
	ds_bpermute_b32 v80, v212, v60
	ds_bpermute_b32 v78, v213, v60
	ds_bpermute_b32 v81, v212, v61
	ds_bpermute_b32 v79, v213, v61
	s_and_saveexec_b64 s[68:69], s[8:9]
	s_xor_b64 s[68:69], exec, s[68:69]
	s_cbranch_execz .LBB0_919
	s_waitcnt lgkmcnt(0)
	v_pk_fma_f32 v[114:115], v[84:85], v[78:79], v[96:97]
	s_nop 0
	v_pk_fma_f32 v[114:115], v[88:89], v[80:81], v[114:115]
	s_nop 0
	v_pk_fma_f32 v[114:115], v[60:61], v[92:93], v[114:115]
	s_nop 0
	v_mul_f32_e32 v116, v115, v115
	v_fmaak_f32 v116, v254, v116, 0xc0135761
	v_mul_f32_e32 v117, v114, v114
	v_mul_f32_e32 v116, v115, v116
	v_fmaak_f32 v117, v254, v117, 0xc0135761
	v_mul_f32_e32 v117, v114, v117
	v_exp_f32_e32 v116, v116
	v_exp_f32_e32 v118, v117
	v_add_f32_e32 v116, 1.0, v116
	v_rcp_f32_e32 v117, v116
	v_add_f32_e32 v116, 1.0, v118
	v_rcp_f32_e32 v116, v116
	s_nop 0
	v_pk_mul_f32 v[114:115], v[114:115], v[116:117]
	v_pk_fma_f32 v[116:117], v[98:99], v[74:75], v[110:111]
	s_nop 0
	v_pk_fma_f32 v[116:117], v[102:103], v[76:77], v[116:117]
	s_nop 0
	v_pk_fma_f32 v[116:117], v[62:63], v[106:107], v[116:117]
	s_nop 0
	v_mul_f32_e32 v118, v116, v116
	v_fmaak_f32 v118, v254, v118, 0xc0135761
	v_mul_f32_e32 v118, v116, v118
	v_exp_f32_e32 v120, v118
	v_mul_f32_e32 v118, v117, v117
	v_fmaak_f32 v118, v254, v118, 0xc0135761
	v_mul_f32_e32 v118, v117, v118
	v_exp_f32_e32 v121, v118
	v_pk_mul_f32 v[118:119], v[52:53], v[114:115]
	v_add_f32_e32 v114, 1.0, v120
	v_rcp_f32_e32 v114, v114
	v_add_f32_e32 v115, 1.0, v121
	v_pk_fma_f32 v[120:121], v[100:101], v[70:71], v[112:113]
	v_rcp_f32_e32 v115, v115
	v_pk_fma_f32 v[120:121], v[104:105], v[72:73], v[120:121]
	v_pk_mul_f32 v[114:115], v[116:117], v[114:115]
	v_pk_fma_f32 v[120:121], v[64:65], v[108:109], v[120:121]
	v_pk_mul_f32 v[114:115], v[54:55], v[114:115]
	v_mul_f32_e32 v122, v120, v120
	v_mul_f32_e32 v123, v121, v121
	v_fmaak_f32 v122, v254, v122, 0xc0135761
	v_fmaak_f32 v123, v254, v123, 0xc0135761
	v_mul_f32_e32 v122, v120, v122
	v_mul_f32_e32 v123, v121, v123
	v_exp_f32_e32 v122, v122
	v_exp_f32_e32 v123, v123
	v_cvt_pk_bf16_f32 v114, v114, v115
	v_add_f32_e32 v116, 1.0, v122
	v_add_f32_e32 v117, 1.0, v123
	v_pk_fma_f32 v[122:123], v[82:83], v[66:67], v[94:95]
	v_rcp_f32_e32 v116, v116
	v_pk_fma_f32 v[122:123], v[86:87], v[68:69], v[122:123]
	v_rcp_f32_e32 v117, v117
	v_pk_fma_f32 v[122:123], v[58:59], v[90:91], v[122:123]
	v_pk_mul_f32 v[116:117], v[120:121], v[116:117]
	v_mul_f32_e32 v124, v123, v123
	v_fmaak_f32 v124, v254, v124, 0xc0135761
	v_mul_f32_e32 v125, v122, v122
	v_mul_f32_e32 v124, v123, v124
	v_fmaak_f32 v125, v254, v125, 0xc0135761
	v_mul_f32_e32 v125, v122, v125
	v_exp_f32_e32 v124, v124
	v_exp_f32_e32 v126, v125
	v_pk_mul_f32 v[116:117], v[56:57], v[116:117]
	v_add_f32_e32 v124, 1.0, v124
	v_rcp_f32_e32 v125, v124
	v_add_f32_e32 v124, 1.0, v126
	v_rcp_f32_e32 v124, v124
	v_cvt_pk_bf16_f32 v115, v116, v117
	v_cvt_pk_bf16_f32 v117, v118, v119
	v_mov_b64_e32 v[118:119], s[10:11]
	v_pk_mul_f32 v[120:121], v[122:123], v[124:125]
	v_add_u32_e32 v122, 0x80, v215
	v_pk_mul_f32 v[120:121], v[50:51], v[120:121]
	v_mad_i64_i32 v[118:119], s[70:71], v122, s79, v[118:119]
	v_cvt_pk_bf16_f32 v116, v120, v121
	v_lshl_add_u64 v[118:119], v[186:187], 1, v[118:119]
	global_store_dwordx4 v[118:119], v[114:117], off

; __device__ __forceinline__ u32x4 pack8(const f32x4 a, const f32x4 b) { u32x4 w; w.x = cvt_pk_bf16(a[0], a[1]); w.y = cvt_pk_bf16(a[2], a[3]); w.z = cvt_pk_bf16(b[0], b[1]); w.w = cvt_pk_bf16(b[2], b[3]); return w; }
;     __device__ __forceinline__ void operator()(const f32x4 (&acc)[2][2][4][2], const Unit& u, int wr, int wc, int fr, int fq) const {
;     ...
;             for (int m = 0; m < 4; ++m) {
;                 f32x4 o[2];
; #pragma unroll
;                 for (int n = 0; n < 2; ++n) { f32x4 r1, r2;
; #pragma unroll
;                     for (int e = 0; e < 4; ++e) { const float a0 = acc[ai][0][m][n][e]; r1[e] = __shfl(a0, src1); r2[e] = __shfl(a0, src2); }
;                     f32x4 a1, a2;
; #pragma unroll
;                     for (int e = 0; e < 4; ++e) { a1[e] = fr >= 1 ? r1[e] : p1[n][e]; a2[e] = fr >= 2 ? r2[e] : p2[n][e]; }
;                     p1[n] = r1; p2[n] = r2;
;                     const f32x4 c = bb[n] + w0[n] * a2 + w1[n] * a1 + w2[n] * acc[ai][0][m][n];
; #pragma unroll
;                     for (int e = 0; e < 4; ++e) { const float x = c[e]; const float uu = 0.7978845608028654f * (x + 0.044715f * x * x * x);
;                         const float gl = x * __builtin_amdgcn_rcpf(1.f + __builtin_amdgcn_exp2f(-2.885390081777927f * uu)); o[n][e] = gl * acc[ai][1][m][n][e]; } }
;                 const int row = u.pm * BM + ai * HALF + wr * 64 + m * 16 + fr;
;                 if (!(m == 0 && fr < 2)) *(u32x4*)(G + (size_t)row * DFF + f0) = pack8(o[0], o[1]);
.LBB0_921:
	s_or_b64 exec, exec, s[68:69]
	ds_bpermute_b32 v63, v213, v45
	ds_bpermute_b32 v64, v213, v44
	ds_bpermute_b32 v61, v212, v45
	ds_bpermute_b32 v62, v212, v44
	ds_bpermute_b32 v55, v213, v46
	s_waitcnt lgkmcnt(4)
	v_cndmask_b32_e64 v53, v79, v63, s[8:9]
	s_waitcnt lgkmcnt(3)
	v_cndmask_b32_e64 v52, v78, v64, s[8:9]
	s_waitcnt lgkmcnt(2)
	v_cndmask_b32_e64 v51, v61, v81, s[0:1]
	s_waitcnt lgkmcnt(1)
	v_cndmask_b32_e64 v50, v62, v80, s[0:1]
	v_pk_fma_f32 v[52:53], v[84:85], v[52:53], v[96:97]
	ds_bpermute_b32 v57, v213, v47
	v_pk_fma_f32 v[50:51], v[88:89], v[50:51], v[52:53]
	ds_bpermute_b32 v54, v212, v46
	v_pk_fma_f32 v[44:45], v[44:45], v[92:93], v[50:51]
	ds_bpermute_b32 v56, v212, v47
	v_mul_f32_e32 v50, v45, v45
	v_fmaak_f32 v50, v254, v50, 0xc0135761
	v_mul_f32_e32 v51, v44, v44
	v_mul_f32_e32 v50, v45, v50
	v_fmaak_f32 v51, v254, v51, 0xc0135761
	v_mul_f32_e32 v51, v44, v51
	v_exp_f32_e32 v50, v50
	v_exp_f32_e32 v52, v51
	s_waitcnt lgkmcnt(2)
	v_cndmask_b32_e64 v53, v75, v57, s[8:9]
	v_add_f32_e32 v50, 1.0, v50
	v_rcp_f32_e32 v51, v50
	v_add_f32_e32 v50, 1.0, v52
	v_rcp_f32_e32 v50, v50
	v_cndmask_b32_e64 v52, v74, v55, s[8:9]
	v_pk_fma_f32 v[52:53], v[98:99], v[52:53], v[110:111]
	ds_bpermute_b32 v59, v213, v48
	v_pk_mul_f32 v[44:45], v[44:45], v[50:51]
	s_waitcnt lgkmcnt(1)
	v_cndmask_b32_e64 v51, v56, v77, s[0:1]
	v_cndmask_b32_e64 v50, v54, v76, s[0:1]
	v_pk_fma_f32 v[50:51], v[102:103], v[50:51], v[52:53]
	ds_bpermute_b32 v65, v213, v49
	v_pk_fma_f32 v[46:47], v[46:47], v[106:107], v[50:51]
	ds_bpermute_b32 v58, v212, v48
	v_mul_f32_e32 v50, v46, v46
	v_mul_f32_e32 v51, v47, v47
	v_fmaak_f32 v50, v254, v50, 0xc0135761
	v_fmaak_f32 v51, v254, v51, 0xc0135761
	v_mul_f32_e32 v50, v46, v50
	v_mul_f32_e32 v51, v47, v51
	ds_bpermute_b32 v60, v212, v49
	v_exp_f32_e32 v50, v50
	v_exp_f32_e32 v51, v51
	s_waitcnt lgkmcnt(2)
	v_cndmask_b32_e64 v53, v71, v65, s[8:9]
	v_cndmask_b32_e64 v52, v70, v59, s[8:9]
	v_pk_mul_f32 v[44:45], v[36:37], v[44:45]
	v_add_f32_e32 v36, 1.0, v50
	v_add_f32_e32 v37, 1.0, v51
	s_waitcnt lgkmcnt(0)
	v_cndmask_b32_e64 v51, v60, v73, s[0:1]
	v_cndmask_b32_e64 v50, v58, v72, s[0:1]
	v_pk_fma_f32 v[52:53], v[100:101], v[52:53], v[112:113]
	ds_bpermute_b32 v79, v213, v42
	v_pk_fma_f32 v[50:51], v[104:105], v[50:51], v[52:53]
	ds_bpermute_b32 v81, v213, v43
	v_pk_fma_f32 v[48:49], v[48:49], v[108:109], v[50:51]
	ds_bpermute_b32 v78, v212, v42
	v_mul_f32_e32 v50, v48, v48
	v_mul_f32_e32 v51, v49, v49
	v_fmaak_f32 v50, v254, v50, 0xc0135761
	v_fmaak_f32 v51, v254, v51, 0xc0135761
	v_mul_f32_e32 v50, v48, v50
	v_mul_f32_e32 v51, v49, v51
	ds_bpermute_b32 v80, v212, v43
	v_rcp_f32_e32 v36, v36
	v_rcp_f32_e32 v37, v37
	v_exp_f32_e32 v50, v50
	v_exp_f32_e32 v51, v51
	s_waitcnt lgkmcnt(2)
	v_cndmask_b32_e64 v53, v67, v81, s[8:9]
	v_cndmask_b32_e64 v52, v66, v79, s[8:9]
	v_pk_mul_f32 v[36:37], v[46:47], v[36:37]
	v_add_f32_e32 v46, 1.0, v50
	v_add_f32_e32 v47, 1.0, v51
	s_waitcnt lgkmcnt(0)
	v_cndmask_b32_e64 v51, v80, v69, s[0:1]
	v_cndmask_b32_e64 v50, v78, v68, s[0:1]
	v_pk_fma_f32 v[52:53], v[82:83], v[52:53], v[94:95]
	v_rcp_f32_e32 v46, v46
	v_pk_fma_f32 v[50:51], v[86:87], v[50:51], v[52:53]
	v_rcp_f32_e32 v47, v47
	v_pk_fma_f32 v[42:43], v[42:43], v[90:91], v[50:51]
	v_pk_mul_f32 v[36:37], v[38:39], v[36:37]
	v_mul_f32_e32 v50, v43, v43
	v_fmaak_f32 v50, v254, v50, 0xc0135761
	v_mul_f32_e32 v51, v42, v42
	v_mul_f32_e32 v50, v43, v50
	v_fmaak_f32 v51, v254, v51, 0xc0135761
	v_mul_f32_e32 v51, v42, v51
	v_exp_f32_e32 v50, v50
	v_exp_f32_e32 v52, v51
	v_pk_mul_f32 v[38:39], v[48:49], v[46:47]
	v_add_f32_e32 v50, 1.0, v50
	v_rcp_f32_e32 v51, v50
	v_add_f32_e32 v50, 1.0, v52
	v_rcp_f32_e32 v50, v50
	v_pk_mul_f32 v[38:39], v[40:41], v[38:39]
	ds_bpermute_b32 v49, v213, v29
	ds_bpermute_b32 v47, v212, v29
	v_pk_mul_f32 v[40:41], v[42:43], v[50:51]
	ds_bpermute_b32 v50, v213, v28
	v_pk_mul_f32 v[34:35], v[34:35], v[40:41]
	ds_bpermute_b32 v48, v212, v28
	v_add_u32_e32 v40, 0x90, v215
	v_cvt_pk_bf16_f32 v36, v36, v37
	v_cvt_pk_bf16_f32 v37, v38, v39
	v_cvt_pk_bf16_f32 v38, v34, v35
	v_mov_b64_e32 v[34:35], s[10:11]
	v_mad_i64_i32 v[40:41], s[68:69], v40, s79, v[34:35]
	v_cvt_pk_bf16_f32 v39, v44, v45
	v_lshl_add_u64 v[40:41], v[40:41], 0, v[130:131]
	global_store_dwordx4 v[40:41], v[36:39], off
	ds_bpermute_b32 v41, v213, v30
	ds_bpermute_b32 v43, v213, v31
	s_waitcnt lgkmcnt(5)
	v_cndmask_b32_e64 v39, v63, v49, s[8:9]
	s_waitcnt lgkmcnt(3)
	v_cndmask_b32_e64 v38, v64, v50, s[8:9]
	v_cndmask_b32_e64 v37, v47, v61, s[0:1]
	s_waitcnt lgkmcnt(2)
	v_cndmask_b32_e64 v36, v48, v62, s[0:1]
	v_pk_fma_f32 v[38:39], v[84:85], v[38:39], v[96:97]
	ds_bpermute_b32 v40, v212, v30
	v_pk_fma_f32 v[36:37], v[88:89], v[36:37], v[38:39]
	ds_bpermute_b32 v42, v212, v31
	v_pk_fma_f32 v[28:29], v[28:29], v[92:93], v[36:37]
	s_waitcnt lgkmcnt(2)
	v_cndmask_b32_e64 v39, v57, v43, s[8:9]
	v_mul_f32_e32 v36, v29, v29
	v_fmaak_f32 v36, v254, v36, 0xc0135761
	v_mul_f32_e32 v37, v28, v28
	v_mul_f32_e32 v36, v29, v36
	v_fmaak_f32 v37, v254, v37, 0xc0135761
	v_mul_f32_e32 v37, v28, v37
	v_exp_f32_e32 v36, v36
	v_exp_f32_e32 v38, v37
	ds_bpermute_b32 v45, v213, v32
	v_add_f32_e32 v36, 1.0, v36
	v_rcp_f32_e32 v37, v36
	v_add_f32_e32 v36, 1.0, v38
	v_rcp_f32_e32 v36, v36
	v_cndmask_b32_e64 v38, v55, v41, s[8:9]
	v_pk_fma_f32 v[38:39], v[98:99], v[38:39], v[110:111]
	ds_bpermute_b32 v51, v213, v33
	v_pk_mul_f32 v[28:29], v[28:29], v[36:37]
	s_waitcnt lgkmcnt(2)
; __device__ __forceinline__ u32x4 pack8(const f32x4 a, const f32x4 b) { u32x4 w; w.x = cvt_pk_bf16(a[0], a[1]); w.y = cvt_pk_bf16(a[2], a[3]); w.z = cvt_pk_bf16(b[0], b[1]); w.w = cvt_pk_bf16(b[2], b[3]); return w; }
;     __device__ __forceinline__ void operator()(const f32x4 (&acc)[2][2][4][2], const Unit& u, int wr, int wc, int fr, int fq) const {
;     ...
;             for (int m = 0; m < 4; ++m) {
;                 f32x4 o[2];
; #pragma unroll
;                 for (int n = 0; n < 2; ++n) { f32x4 r1, r2;
; #pragma unroll
;                     for (int e = 0; e < 4; ++e) { const float a0 = acc[ai][0][m][n][e]; r1[e] = __shfl(a0, src1); r2[e] = __shfl(a0, src2); }
;                     f32x4 a1, a2;
; #pragma unroll
;                     for (int e = 0; e < 4; ++e) { a1[e] = fr >= 1 ? r1[e] : p1[n][e]; a2[e] = fr >= 2 ? r2[e] : p2[n][e]; }
;                     p1[n] = r1; p2[n] = r2;
;                     const f32x4 c = bb[n] + w0[n] * a2 + w1[n] * a1 + w2[n] * acc[ai][0][m][n];
; #pragma unroll
;                     for (int e = 0; e < 4; ++e) { const float x = c[e]; const float uu = 0.7978845608028654f * (x + 0.044715f * x * x * x);
;                         const float gl = x * __builtin_amdgcn_rcpf(1.f + __builtin_amdgcn_exp2f(-2.885390081777927f * uu)); o[n][e] = gl * acc[ai][1][m][n][e]; } }
;                 const int row = u.pm * BM + ai * HALF + wr * 64 + m * 16 + fr;
;                 if (!(m == 0 && fr < 2)) *(u32x4*)(G + (size_t)row * DFF + f0) = pack8(o[0], o[1]);
;                 if (m == 0 && fr < 2) { float* ah = AH + ((size_t)jb * 4 + 2 + fr) * DFF + f0; *(f32x4*)ah = acc[ai][0][0][0]; *(f32x4*)(ah + 4) = acc[ai][0][0][1];
;                     float* bh = BH + ((size_t)jb * 2 + fr) * DFF + f0; *(f32x4*)bh = acc[ai][1][0][0]; *(f32x4*)(bh + 4) = acc[ai][1][0][1]; }
;                 if (m == 3 && fr >= 14) { float* ah = AH + ((size_t)jb * 4 + (fr - 14)) * DFF + f0; *(f32x4*)ah = acc[ai][0][3][0]; *(f32x4*)(ah + 4) = acc[ai][0][3][1]; }
	v_cndmask_b32_e64 v37, v42, v56, s[0:1]
	v_cndmask_b32_e64 v36, v40, v54, s[0:1]
	v_pk_fma_f32 v[36:37], v[102:103], v[36:37], v[38:39]
	ds_bpermute_b32 v44, v212, v32
	v_pk_fma_f32 v[30:31], v[30:31], v[106:107], v[36:37]
	ds_bpermute_b32 v46, v212, v33
	v_mul_f32_e32 v36, v30, v30
	v_mul_f32_e32 v37, v31, v31
	v_fmaak_f32 v36, v254, v36, 0xc0135761
	v_fmaak_f32 v37, v254, v37, 0xc0135761
	v_mul_f32_e32 v36, v30, v36
	v_mul_f32_e32 v37, v31, v37
	v_exp_f32_e32 v36, v36
	v_exp_f32_e32 v37, v37
	s_waitcnt lgkmcnt(2)
	v_cndmask_b32_e64 v39, v65, v51, s[8:9]
	v_cndmask_b32_e64 v38, v59, v45, s[8:9]
	v_pk_mul_f32 v[28:29], v[20:21], v[28:29]
	v_add_f32_e32 v20, 1.0, v36
	v_add_f32_e32 v21, 1.0, v37
	s_waitcnt lgkmcnt(0)
	v_cndmask_b32_e64 v37, v46, v60, s[0:1]
	v_cndmask_b32_e64 v36, v44, v58, s[0:1]
	v_pk_fma_f32 v[38:39], v[100:101], v[38:39], v[112:113]
	ds_bpermute_b32 v53, v213, v26
	v_pk_fma_f32 v[36:37], v[104:105], v[36:37], v[38:39]
	ds_bpermute_b32 v62, v213, v27
	v_pk_fma_f32 v[32:33], v[32:33], v[108:109], v[36:37]
	ds_bpermute_b32 v52, v212, v26
	v_mul_f32_e32 v36, v32, v32
	v_mul_f32_e32 v37, v33, v33
	v_fmaak_f32 v36, v254, v36, 0xc0135761
	v_fmaak_f32 v37, v254, v37, 0xc0135761
	v_mul_f32_e32 v36, v32, v36
	v_mul_f32_e32 v37, v33, v37
	ds_bpermute_b32 v61, v212, v27
	v_rcp_f32_e32 v20, v20
	v_rcp_f32_e32 v21, v21
	v_exp_f32_e32 v36, v36
	v_exp_f32_e32 v37, v37
	s_waitcnt lgkmcnt(2)
	v_cndmask_b32_e64 v39, v81, v62, s[8:9]
	v_cndmask_b32_e64 v38, v79, v53, s[8:9]
	v_pk_mul_f32 v[20:21], v[30:31], v[20:21]
	v_add_f32_e32 v30, 1.0, v36
	v_add_f32_e32 v31, 1.0, v37
	s_waitcnt lgkmcnt(0)
	v_cndmask_b32_e64 v37, v61, v80, s[0:1]
	v_cndmask_b32_e64 v36, v52, v78, s[0:1]
	v_pk_fma_f32 v[38:39], v[82:83], v[38:39], v[94:95]
	v_rcp_f32_e32 v30, v30
	v_pk_fma_f32 v[36:37], v[86:87], v[36:37], v[38:39]
	v_rcp_f32_e32 v31, v31
	v_pk_fma_f32 v[26:27], v[26:27], v[90:91], v[36:37]
	v_pk_mul_f32 v[20:21], v[22:23], v[20:21]
	v_mul_f32_e32 v36, v27, v27
	v_fmaak_f32 v36, v254, v36, 0xc0135761
	v_mul_f32_e32 v37, v26, v26
	v_mul_f32_e32 v36, v27, v36
	v_fmaak_f32 v37, v254, v37, 0xc0135761
	v_mul_f32_e32 v37, v26, v37
	v_exp_f32_e32 v36, v36
	v_exp_f32_e32 v38, v37
	v_pk_mul_f32 v[22:23], v[32:33], v[30:31]
	v_add_f32_e32 v36, 1.0, v36
	v_rcp_f32_e32 v37, v36
	v_add_f32_e32 v36, 1.0, v38
	v_rcp_f32_e32 v36, v36
	v_pk_mul_f32 v[22:23], v[24:25], v[22:23]
	ds_bpermute_b32 v31, v213, v8
	ds_bpermute_b32 v33, v213, v9
	v_pk_mul_f32 v[24:25], v[26:27], v[36:37]
	v_add_u32_e32 v26, 0xa0, v215
	v_pk_mul_f32 v[24:25], v[18:19], v[24:25]
	v_cvt_pk_bf16_f32 v19, v22, v23
	v_mad_i64_i32 v[22:23], s[68:69], v26, s79, v[34:35]
	v_cvt_pk_bf16_f32 v18, v20, v21
	v_cvt_pk_bf16_f32 v20, v24, v25
	v_cvt_pk_bf16_f32 v21, v28, v29
	v_lshl_add_u64 v[22:23], v[22:23], 0, v[130:131]
	global_store_dwordx4 v[22:23], v[18:21], off
	ds_bpermute_b32 v20, v213, v10
	ds_bpermute_b32 v21, v213, v11
	ds_bpermute_b32 v18, v212, v10
	ds_bpermute_b32 v19, v212, v11
	ds_bpermute_b32 v22, v212, v12
	s_waitcnt lgkmcnt(4)
	v_cndmask_b32_e64 v20, v41, v20, s[8:9]
	s_waitcnt lgkmcnt(3)
	v_cndmask_b32_e64 v21, v43, v21, s[8:9]
	s_waitcnt lgkmcnt(2)
	v_cndmask_b32_e64 v18, v18, v40, s[0:1]
	s_waitcnt lgkmcnt(1)
	v_cndmask_b32_e64 v19, v19, v42, s[0:1]
	v_pk_fma_f32 v[20:21], v[98:99], v[20:21], v[110:111]
	ds_bpermute_b32 v24, v213, v12
	v_pk_fma_f32 v[18:19], v[102:103], v[18:19], v[20:21]
	ds_bpermute_b32 v23, v212, v13
	v_pk_fma_f32 v[18:19], v[10:11], v[106:107], v[18:19]
	ds_bpermute_b32 v25, v213, v13
	v_mul_f32_e32 v20, v18, v18
	v_mul_f32_e32 v21, v19, v19
	v_fmaak_f32 v20, v254, v20, 0xc0135761
	v_fmaak_f32 v21, v254, v21, 0xc0135761
	v_mul_f32_e32 v20, v18, v20
	v_mul_f32_e32 v21, v19, v21
	v_exp_f32_e32 v20, v20
	v_exp_f32_e32 v21, v21
	ds_bpermute_b32 v27, v213, v6
	ds_bpermute_b32 v29, v213, v7
	v_add_f32_e32 v20, 1.0, v20
	v_add_f32_e32 v21, 1.0, v21
	v_rcp_f32_e32 v20, v20
	v_rcp_f32_e32 v21, v21
	ds_bpermute_b32 v26, v212, v6
	ds_bpermute_b32 v28, v212, v7
	ds_bpermute_b32 v30, v212, v8
	v_pk_mul_f32 v[18:19], v[18:19], v[20:21]
	s_waitcnt lgkmcnt(6)
	v_cndmask_b32_e64 v21, v23, v46, s[0:1]
	v_cndmask_b32_e64 v20, v22, v44, s[0:1]
	s_waitcnt lgkmcnt(5)
	v_cndmask_b32_e64 v23, v51, v25, s[8:9]
	v_cndmask_b32_e64 v22, v45, v24, s[8:9]
	v_pk_fma_f32 v[22:23], v[100:101], v[22:23], v[112:113]
	s_waitcnt lgkmcnt(3)
	v_cndmask_b32_e64 v25, v62, v29, s[8:9]
	v_pk_fma_f32 v[20:21], v[104:105], v[20:21], v[22:23]
	v_cndmask_b32_e64 v24, v53, v27, s[8:9]
	v_pk_fma_f32 v[20:21], v[12:13], v[108:109], v[20:21]
	v_pk_mul_f32 v[14:15], v[14:15], v[18:19]
	v_mul_f32_e32 v22, v20, v20
	v_mul_f32_e32 v23, v21, v21
	v_fmaak_f32 v22, v254, v22, 0xc0135761
	v_fmaak_f32 v23, v254, v23, 0xc0135761
	v_mul_f32_e32 v22, v20, v22
	v_mul_f32_e32 v23, v21, v23
	v_exp_f32_e32 v22, v22
	v_exp_f32_e32 v23, v23
	v_pk_fma_f32 v[24:25], v[82:83], v[24:25], v[94:95]
	ds_bpermute_b32 v32, v212, v9
	v_add_f32_e32 v18, 1.0, v22
	v_add_f32_e32 v19, 1.0, v23
	s_waitcnt lgkmcnt(2)
	v_cndmask_b32_e64 v23, v28, v61, s[0:1]
	v_cndmask_b32_e64 v22, v26, v52, s[0:1]
	v_pk_fma_f32 v[22:23], v[86:87], v[22:23], v[24:25]
	v_rcp_f32_e32 v18, v18
	v_pk_fma_f32 v[22:23], v[6:7], v[90:91], v[22:23]
	v_rcp_f32_e32 v19, v19
	v_mul_f32_e32 v24, v22, v22
	v_mul_f32_e32 v25, v23, v23
	v_fmaak_f32 v24, v254, v24, 0xc0135761
	v_fmaak_f32 v25, v254, v25, 0xc0135761
	v_mul_f32_e32 v24, v22, v24
	v_mul_f32_e32 v25, v23, v25
	v_exp_f32_e32 v24, v24
	v_exp_f32_e32 v25, v25
	v_cndmask_b32_e64 v27, v49, v33, s[8:9]
	v_cndmask_b32_e64 v26, v50, v31, s[8:9]
	v_pk_mul_f32 v[18:19], v[20:21], v[18:19]
	v_add_f32_e32 v20, 1.0, v24
	v_add_f32_e32 v21, 1.0, v25
	s_waitcnt lgkmcnt(0)
	v_cndmask_b32_e64 v25, v32, v47, s[0:1]
	v_cndmask_b32_e64 v24, v30, v48, s[0:1]
	v_pk_fma_f32 v[26:27], v[84:85], v[26:27], v[96:97]
	v_rcp_f32_e32 v20, v20
	v_pk_fma_f32 v[24:25], v[88:89], v[24:25], v[26:27]
	v_rcp_f32_e32 v21, v21
	v_pk_fma_f32 v[24:25], v[8:9], v[92:93], v[24:25]
	v_pk_mul_f32 v[16:17], v[16:17], v[18:19]
	v_mul_f32_e32 v26, v25, v25
	v_fmaak_f32 v26, v254, v26, 0xc0135761
	v_mul_f32_e32 v27, v24, v24
	v_mul_f32_e32 v26, v25, v26
	v_fmaak_f32 v27, v254, v27, 0xc0135761
	v_mul_f32_e32 v27, v24, v27
	v_exp_f32_e32 v26, v26
	v_exp_f32_e32 v28, v27
	v_pk_mul_f32 v[18:19], v[22:23], v[20:21]
	v_add_f32_e32 v26, 1.0, v26
	v_rcp_f32_e32 v27, v26
	v_add_f32_e32 v26, 1.0, v28
	v_rcp_f32_e32 v26, v26
	v_pk_mul_f32 v[18:19], v[2:3], v[18:19]
	v_add_u32_e32 v22, 0xb0, v215
	v_pk_mul_f32 v[2:3], v[24:25], v[26:27]
	s_nop 0
	v_pk_mul_f32 v[20:21], v[4:5], v[2:3]
	v_cvt_pk_bf16_f32 v2, v14, v15
	v_mad_i64_i32 v[14:15], s[68:69], v22, s79, v[34:35]
	v_cvt_pk_bf16_f32 v3, v16, v17
	v_cvt_pk_bf16_f32 v4, v18, v19
	v_cvt_pk_bf16_f32 v5, v20, v21
	v_lshl_add_u64 v[14:15], v[14:15], 0, v[130:131]
	global_store_dwordx4 v[14:15], v[2:5], off
	s_and_saveexec_b64 s[68:69], s[4:5]
	s_cbranch_execz .LBB0_923
;     __device__ __forceinline__ void operator()(const f32x4 (&acc)[2][2][4][2], const Unit& u, int wr, int wc, int fr, int fq) const {
;     ...
;                 if (m == 3 && fr >= 14) { float* ah = AH + ((size_t)jb * 4 + (fr - 14)) * DFF + f0; *(f32x4*)ah = acc[ai][0][3][0]; *(f32x4*)(ah + 4) = acc[ai][0][3][1]; }
	v_lshl_add_u64 v[2:3], s[66:67], 0, v[176:177]
	v_mov_b64_e32 v[4:5], s[14:15]
	v_mad_u64_u32 v[4:5], s[66:67], v2, s80, v[4:5]
	v_mad_i32_i24 v5, v3, s80, v5
	v_lshl_add_u64 v[2:3], v[186:187], 2, v[4:5]
	global_store_dwordx4 v[2:3], v[10:13], off
	global_store_dwordx4 v[2:3], v[6:9], off offset:16

; __global__ void __launch_bounds__(512) fwd_mega(Args a) {
;     ...
;     if (IN(9)) {
;         constexpr int NF4 = DFF / 4;
;         for (int i = bx * 512 + tid; i < 1024 * NF4; i += G * 512) { const int f = (i % NF4) * 4, rj = i / NF4, jb = rj >> 1, ii = rj & 1; const bool first = (jb & 255) == 0;
.LBB0_943:
	s_cmp_lt_i32 s54, 10
	s_cselect_b64 s[4:5], -1, 0
	s_and_b64 s[4:5], s[4:5], s[0:1]
	s_andn2_b64 vcc, exec, s[4:5]
	s_cbranch_vccnz .LBB0_954
	v_mov_b32_e32 v254, 0xbdd2d3e7
	s_mov_b64 s[6:7], exec
	s_add_u32 s8, s24, 0x5800
	s_addc_u32 s9, s25, 0
	s_add_u32 s0, s24, 0xb000
	s_addc_u32 s1, s25, 0
	v_lshlrev_b32_e32 v2, 4, v206
	v_lshlrev_b32_e32 v3, 3, v206
	v_readfirstlane_b32 s2, v162
	s_nop 3
	s_and_b32 s2, s2, 0x3c0
	s_lshl_b32 s36, s60, 9
	s_add_u32 s2, s2, s36
	s_lshl_b32 s16, s3, 9
	s_mov_b32 s28, s2
	s_cmp_lt_u32 s2, 1441792
	s_cbranch_scc0 .Lp9_done

; __device__ __forceinline__ unsigned pk2(float lo, float hi) { return f2bf(lo) | (f2bf(hi) << 16); }
; __global__ void __launch_bounds__(512) fwd_mega(Args a) {
;     ...
;             const f32x4 c = *(const f32x4*)(a.conv_b + f) + *(const f32x4*)(a.conv_w + f) * a2 + *(const f32x4*)(a.conv_w + DFF + f) * a1 + *(const f32x4*)(a.conv_w + 2 * DFF + f) * a0;
;             float o[4];
; #pragma unroll
;             for (int e = 0; e < 4; ++e) { const float x = c[e]; const float uu = 0.7978845608028654f * (x + 0.044715f * x * x * x);
;                 o[e] = x * __builtin_amdgcn_rcpf(1.f + __builtin_amdgcn_exp2f(-2.885390081777927f * uu)) * bv[e]; }
;             *(unsigned long long*)(GG + ((size_t)jb * 64 + ii) * DFF + f) = (unsigned long long)pk2(o[0], o[1]) | ((unsigned long long)pk2(o[2], o[3]) << 32); }
.Lp9_z0b:
	v_pk_fma_f32 v[16:17], v[20:21], v[32:33], v[16:17]
	v_pk_fma_f32 v[18:19], v[22:23], v[34:35], v[18:19]
	v_pk_fma_f32 v[16:17], v[24:25], v[36:37], v[16:17]
	v_pk_fma_f32 v[18:19], v[26:27], v[38:39], v[18:19]
	v_pk_fma_f32 v[16:17], v[28:29], v[40:41], v[16:17]
	v_pk_fma_f32 v[18:19], v[30:31], v[42:43], v[18:19]
	v_mul_f32_e32 v20, v16, v16
	v_mul_f32_e32 v21, v17, v17
	v_mul_f32_e32 v22, v18, v18
	v_mul_f32_e32 v23, v19, v19
	v_fmaak_f32 v20, v254, v20, 0xc0135761
	v_fmaak_f32 v21, v254, v21, 0xc0135761
	v_fmaak_f32 v22, v254, v22, 0xc0135761
	v_fmaak_f32 v23, v254, v23, 0xc0135761
	v_mul_f32_e32 v20, v16, v20
	v_mul_f32_e32 v21, v17, v21
	v_mul_f32_e32 v22, v18, v22
	v_mul_f32_e32 v23, v19, v23
	v_exp_f32_e32 v20, v20
	v_exp_f32_e32 v21, v21
	v_exp_f32_e32 v22, v22
	v_exp_f32_e32 v23, v23
	s_nop 0
	v_add_f32_e32 v20, 1.0, v20
	v_add_f32_e32 v21, 1.0, v21
	v_add_f32_e32 v22, 1.0, v22
	v_add_f32_e32 v23, 1.0, v23
	v_rcp_f32_e32 v20, v20
	v_rcp_f32_e32 v21, v21
	v_rcp_f32_e32 v22, v22
	v_rcp_f32_e32 v23, v23
	s_nop 0
	v_pk_mul_f32 v[16:17], v[16:17], v[20:21]
	v_pk_mul_f32 v[18:19], v[18:19], v[22:23]
	v_pk_mul_f32 v[16:17], v[44:45], v[16:17]
	v_pk_mul_f32 v[18:19], v[46:47], v[18:19]
	v_cvt_pk_bf16_f32 v16, v16, v17
	v_cvt_pk_bf16_f32 v17, v18, v19
	global_store_dwordx2 v144, v[16:17], s[52:53]
	v_readlane_b32 s36, v4, 2
	v_readlane_b32 s37, v4, 3
	s_nop 3
	s_cmp_eq_u32 s36, 0
	s_cbranch_scc1 .Lp9_z1a
	v_mov_b32_e32 v64, 0
	v_mov_b32_e32 v65, 0
	v_mov_b32_e32 v66, 0
	v_mov_b32_e32 v67, 0

; __device__ __forceinline__ unsigned pk2(float lo, float hi) { return f2bf(lo) | (f2bf(hi) << 16); }
; __global__ void __launch_bounds__(512) fwd_mega(Args a) {
;     ...
;             const f32x4 c = *(const f32x4*)(a.conv_b + f) + *(const f32x4*)(a.conv_w + f) * a2 + *(const f32x4*)(a.conv_w + DFF + f) * a1 + *(const f32x4*)(a.conv_w + 2 * DFF + f) * a0;
;             float o[4];
; #pragma unroll
;             for (int e = 0; e < 4; ++e) { const float x = c[e]; const float uu = 0.7978845608028654f * (x + 0.044715f * x * x * x);
;                 o[e] = x * __builtin_amdgcn_rcpf(1.f + __builtin_amdgcn_exp2f(-2.885390081777927f * uu)) * bv[e]; }
;             *(unsigned long long*)(GG + ((size_t)jb * 64 + ii) * DFF + f) = (unsigned long long)pk2(o[0], o[1]) | ((unsigned long long)pk2(o[2], o[3]) << 32); }
.Lp9_z1b:
	v_pk_fma_f32 v[48:49], v[52:53], v[64:65], v[48:49]
	v_pk_fma_f32 v[50:51], v[54:55], v[66:67], v[50:51]
	v_pk_fma_f32 v[48:49], v[56:57], v[68:69], v[48:49]
	v_pk_fma_f32 v[50:51], v[58:59], v[70:71], v[50:51]
	v_pk_fma_f32 v[48:49], v[60:61], v[72:73], v[48:49]
	v_pk_fma_f32 v[50:51], v[62:63], v[74:75], v[50:51]
	v_mul_f32_e32 v52, v48, v48
	v_mul_f32_e32 v53, v49, v49
	v_mul_f32_e32 v54, v50, v50
	v_mul_f32_e32 v55, v51, v51
	v_fmaak_f32 v52, v254, v52, 0xc0135761
	v_fmaak_f32 v53, v254, v53, 0xc0135761
	v_fmaak_f32 v54, v254, v54, 0xc0135761
	v_fmaak_f32 v55, v254, v55, 0xc0135761
	v_mul_f32_e32 v52, v48, v52
	v_mul_f32_e32 v53, v49, v53
	v_mul_f32_e32 v54, v50, v54
	v_mul_f32_e32 v55, v51, v55
	v_exp_f32_e32 v52, v52
	v_exp_f32_e32 v53, v53
	v_exp_f32_e32 v54, v54
	v_exp_f32_e32 v55, v55
	s_nop 0
	v_add_f32_e32 v52, 1.0, v52
	v_add_f32_e32 v53, 1.0, v53
	v_add_f32_e32 v54, 1.0, v54
	v_add_f32_e32 v55, 1.0, v55
	v_rcp_f32_e32 v52, v52
	v_rcp_f32_e32 v53, v53
	v_rcp_f32_e32 v54, v54
	v_rcp_f32_e32 v55, v55
	s_nop 0
	v_pk_mul_f32 v[48:49], v[48:49], v[52:53]
	v_pk_mul_f32 v[50:51], v[50:51], v[54:55]
	v_pk_mul_f32 v[48:49], v[76:77], v[48:49]
	v_pk_mul_f32 v[50:51], v[78:79], v[50:51]
	v_cvt_pk_bf16_f32 v48, v48, v49
	v_cvt_pk_bf16_f32 v49, v50, v51
	global_store_dwordx2 v145, v[48:49], s[52:53]
	v_readlane_b32 s36, v4, 4
	v_readlane_b32 s37, v4, 5
	s_nop 3
	s_cmp_eq_u32 s36, 0
	s_cbranch_scc1 .Lp9_z2a
	v_mov_b32_e32 v96, 0
	v_mov_b32_e32 v97, 0
	v_mov_b32_e32 v98, 0
	v_mov_b32_e32 v99, 0

; __device__ __forceinline__ unsigned pk2(float lo, float hi) { return f2bf(lo) | (f2bf(hi) << 16); }
; __global__ void __launch_bounds__(512) fwd_mega(Args a) {
;     ...
;             const f32x4 c = *(const f32x4*)(a.conv_b + f) + *(const f32x4*)(a.conv_w + f) * a2 + *(const f32x4*)(a.conv_w + DFF + f) * a1 + *(const f32x4*)(a.conv_w + 2 * DFF + f) * a0;
;             float o[4];
; #pragma unroll
;             for (int e = 0; e < 4; ++e) { const float x = c[e]; const float uu = 0.7978845608028654f * (x + 0.044715f * x * x * x);
;                 o[e] = x * __builtin_amdgcn_rcpf(1.f + __builtin_amdgcn_exp2f(-2.885390081777927f * uu)) * bv[e]; }
;             *(unsigned long long*)(GG + ((size_t)jb * 64 + ii) * DFF + f) = (unsigned long long)pk2(o[0], o[1]) | ((unsigned long long)pk2(o[2], o[3]) << 32); }
.Lp9_z2b:
	v_pk_fma_f32 v[80:81], v[84:85], v[96:97], v[80:81]
	v_pk_fma_f32 v[82:83], v[86:87], v[98:99], v[82:83]
	v_pk_fma_f32 v[80:81], v[88:89], v[100:101], v[80:81]
	v_pk_fma_f32 v[82:83], v[90:91], v[102:103], v[82:83]
	v_pk_fma_f32 v[80:81], v[92:93], v[104:105], v[80:81]
	v_pk_fma_f32 v[82:83], v[94:95], v[106:107], v[82:83]
	v_mul_f32_e32 v84, v80, v80
	v_mul_f32_e32 v85, v81, v81
	v_mul_f32_e32 v86, v82, v82
	v_mul_f32_e32 v87, v83, v83
	v_fmaak_f32 v84, v254, v84, 0xc0135761
	v_fmaak_f32 v85, v254, v85, 0xc0135761
	v_fmaak_f32 v86, v254, v86, 0xc0135761
	v_fmaak_f32 v87, v254, v87, 0xc0135761
	v_mul_f32_e32 v84, v80, v84
	v_mul_f32_e32 v85, v81, v85
	v_mul_f32_e32 v86, v82, v86
	v_mul_f32_e32 v87, v83, v87
	v_exp_f32_e32 v84, v84
	v_exp_f32_e32 v85, v85
	v_exp_f32_e32 v86, v86
	v_exp_f32_e32 v87, v87
	s_nop 0
	v_add_f32_e32 v84, 1.0, v84
	v_add_f32_e32 v85, 1.0, v85
	v_add_f32_e32 v86, 1.0, v86
	v_add_f32_e32 v87, 1.0, v87
	v_rcp_f32_e32 v84, v84
	v_rcp_f32_e32 v85, v85
	v_rcp_f32_e32 v86, v86
	v_rcp_f32_e32 v87, v87
	s_nop 0
	v_pk_mul_f32 v[80:81], v[80:81], v[84:85]
	v_pk_mul_f32 v[82:83], v[82:83], v[86:87]
	v_pk_mul_f32 v[80:81], v[108:109], v[80:81]
	v_pk_mul_f32 v[82:83], v[110:111], v[82:83]
	v_cvt_pk_bf16_f32 v80, v80, v81
	v_cvt_pk_bf16_f32 v81, v82, v83
	global_store_dwordx2 v146, v[80:81], s[52:53]
	v_readlane_b32 s36, v4, 6
	v_readlane_b32 s37, v4, 7
	s_nop 3
	s_cmp_eq_u32 s36, 0
	s_cbranch_scc1 .Lp9_z3a
	v_mov_b32_e32 v128, 0
	v_mov_b32_e32 v129, 0
	v_mov_b32_e32 v130, 0
	v_mov_b32_e32 v131, 0

; __device__ __forceinline__ unsigned pk2(float lo, float hi) { return f2bf(lo) | (f2bf(hi) << 16); }
; __global__ void __launch_bounds__(512) fwd_mega(Args a) {
;     ...
;             const f32x4 c = *(const f32x4*)(a.conv_b + f) + *(const f32x4*)(a.conv_w + f) * a2 + *(const f32x4*)(a.conv_w + DFF + f) * a1 + *(const f32x4*)(a.conv_w + 2 * DFF + f) * a0;
;             float o[4];
; #pragma unroll
;             for (int e = 0; e < 4; ++e) { const float x = c[e]; const float uu = 0.7978845608028654f * (x + 0.044715f * x * x * x);
;                 o[e] = x * __builtin_amdgcn_rcpf(1.f + __builtin_amdgcn_exp2f(-2.885390081777927f * uu)) * bv[e]; }
;             *(unsigned long long*)(GG + ((size_t)jb * 64 + ii) * DFF + f) = (unsigned long long)pk2(o[0], o[1]) | ((unsigned long long)pk2(o[2], o[3]) << 32); }
.Lp9_z3b:
	v_pk_fma_f32 v[112:113], v[116:117], v[128:129], v[112:113]
	v_pk_fma_f32 v[114:115], v[118:119], v[130:131], v[114:115]
	v_pk_fma_f32 v[112:113], v[120:121], v[132:133], v[112:113]
	v_pk_fma_f32 v[114:115], v[122:123], v[134:135], v[114:115]
	v_pk_fma_f32 v[112:113], v[124:125], v[136:137], v[112:113]
	v_pk_fma_f32 v[114:115], v[126:127], v[138:139], v[114:115]
	v_mul_f32_e32 v116, v112, v112
	v_mul_f32_e32 v117, v113, v113
	v_mul_f32_e32 v118, v114, v114
	v_mul_f32_e32 v119, v115, v115
	v_fmaak_f32 v116, v254, v116, 0xc0135761
	v_fmaak_f32 v117, v254, v117, 0xc0135761
	v_fmaak_f32 v118, v254, v118, 0xc0135761
	v_fmaak_f32 v119, v254, v119, 0xc0135761
	v_mul_f32_e32 v116, v112, v116
	v_mul_f32_e32 v117, v113, v117
	v_mul_f32_e32 v118, v114, v118
	v_mul_f32_e32 v119, v115, v119
	v_exp_f32_e32 v116, v116
	v_exp_f32_e32 v117, v117
	v_exp_f32_e32 v118, v118
	v_exp_f32_e32 v119, v119
	s_nop 0
	v_add_f32_e32 v116, 1.0, v116
	v_add_f32_e32 v117, 1.0, v117
	v_add_f32_e32 v118, 1.0, v118
	v_add_f32_e32 v119, 1.0, v119
	v_rcp_f32_e32 v116, v116
	v_rcp_f32_e32 v117, v117
	v_rcp_f32_e32 v118, v118
	v_rcp_f32_e32 v119, v119
	s_nop 0
	v_pk_mul_f32 v[112:113], v[112:113], v[116:117]
	v_pk_mul_f32 v[114:115], v[114:115], v[118:119]
	v_pk_mul_f32 v[112:113], v[140:141], v[112:113]
	v_pk_mul_f32 v[114:115], v[142:143], v[114:115]
	v_cvt_pk_bf16_f32 v112, v112, v113
	v_cvt_pk_bf16_f32 v113, v114, v115
	global_store_dwordx2 v147, v[112:113], s[52:53]
	s_lshl_b32 s36, s16, 2
	s_add_u32 s2, s2, s36
	s_cmp_lt_u32 s2, 1441792
	s_cbranch_scc1 .Lp9_batch
